# P5 rope-epilogue table loads software-pipelined (3-slot ring, lookahead 2)
# speedup vs baseline: 1.0245x; 1.0029x over previous
.LBB0_786:
	v_lshlrev_b64 v[20:21], 2, v[184:185]
	s_waitcnt lgkmcnt(0)
	v_lshl_add_u64 v[22:23], s[38:39], 0, v[20:21]
	v_lshl_add_u64 v[20:21], s[40:41], 0, v[20:21]
	v_lshlrev_b64 v[128:129], 7, v[182:183]
	v_lshl_add_u64 v[108:109], v[22:23], 0, v[128:129]
	v_lshl_add_u64 v[132:133], v[20:21], 0, v[128:129]
	v_lshlrev_b64 v[252:253], 7, v[182:183]
	v_lshl_add_u64 v[252:253], v[252:253], 0, v[22:23]
	global_load_dwordx4 v[194:197], v[252:253], off offset:16
	global_load_dwordx4 v[198:201], v[252:253], off
	s_mov_b64 s[98:99], 0x400000
	v_lshl_add_u64 v[252:253], v[252:253], 0, s[98:99]
	global_load_dwordx4 v[202:205], v[252:253], off offset:16
	global_load_dwordx4 v[206:209], v[252:253], off
	v_lshlrev_b64 v[252:253], 7, v[180:181]
	v_lshl_add_u64 v[252:253], v[252:253], 0, v[22:23]
	global_load_dwordx4 v[220:223], v[252:253], off offset:16
	global_load_dwordx4 v[224:227], v[252:253], off
	s_mov_b64 s[98:99], 0x400000
	v_lshl_add_u64 v[252:253], v[252:253], 0, s[98:99]
	global_load_dwordx4 v[228:231], v[252:253], off offset:16
	global_load_dwordx4 v[232:235], v[252:253], off
	v_lshlrev_b64 v[252:253], 7, v[178:179]
	v_lshl_add_u64 v[252:253], v[252:253], 0, v[22:23]
	global_load_dwordx4 v[236:239], v[252:253], off offset:16
	global_load_dwordx4 v[240:243], v[252:253], off
	s_mov_b64 s[98:99], 0x400000
	v_lshl_add_u64 v[252:253], v[252:253], 0, s[98:99]
	global_load_dwordx4 v[244:247], v[252:253], off offset:16
	global_load_dwordx4 v[248:251], v[252:253], off
	s_nop 0
	s_nop 0
	s_nop 0
	s_cmp_lt_i32 s10, 2
	s_cselect_b64 vcc, -1, 0
	s_and_b64 s[4:5], vcc, exec
	s_brev_b32 s3, 16
	s_cselect_b32 s3, s3, 0xa000000
	v_readlane_b32 s4, v254, 8
	v_readlane_b32 s5, v254, 9
	s_add_u32 s4, s4, s3
	s_addc_u32 s5, s5, 0
	s_and_b32 s2, s2, 0x100
	s_or_b32 s2, s2, s78
	v_add_u32_e32 v16, s2, v184
	v_cndmask_b32_e32 v18, 1.0, v219, vcc
	v_ashrrev_i32_e32 v17, 31, v16
	v_lshl_add_u64 v[16:17], v[16:17], 1, s[4:5]
	v_readlane_b32 s6, v254, 10
	v_readlane_b32 s7, v254, 11
	s_waitcnt vmcnt(8)
	v_pk_mul_f32 v[142:143], v[150:151], v[202:203]
	v_pk_mul_f32 v[128:129], v[146:147], v[202:203]
	s_waitcnt vmcnt(8)
	v_pk_mul_f32 v[136:137], v[190:191], v[208:209]
	v_pk_mul_f32 v[138:139], v[192:193], v[206:207]
	v_pk_mul_f32 v[140:141], v[148:149], v[204:205]
	v_pk_fma_f32 v[142:143], v[146:147], v[194:195], v[142:143] neg_lo:[0,0,1] neg_hi:[0,0,1]
	v_pk_mul_f32 v[130:131], v[144:145], v[204:205]
	v_pk_fma_f32 v[40:41], v[150:151], v[194:195], v[128:129]
	v_pk_fma_f32 v[136:137], v[186:187], v[200:201], v[136:137] neg_lo:[0,0,1] neg_hi:[0,0,1]
	v_pk_fma_f32 v[138:139], v[188:189], v[198:199], v[138:139] neg_lo:[0,0,1] neg_hi:[0,0,1]
	v_pk_fma_f32 v[140:141], v[144:145], v[196:197], v[140:141] neg_lo:[0,0,1] neg_hi:[0,0,1]
	v_pk_mul_f32 v[134:135], v[186:187], v[208:209]
	v_pk_mul_f32 v[132:133], v[188:189], v[206:207]
	v_pk_fma_f32 v[42:43], v[148:149], v[196:197], v[130:131]
	v_pk_mul_f32 v[130:131], v[18:19], v[40:41] op_sel_hi:[0,1]
	v_lshlrev_b64 v[40:41], 10, v[182:183]
	v_pk_mul_f32 v[136:137], v[18:19], v[136:137] op_sel_hi:[0,1]
	v_pk_mul_f32 v[138:139], v[18:19], v[138:139] op_sel_hi:[0,1]
	v_pk_mul_f32 v[140:141], v[18:19], v[140:141] op_sel_hi:[0,1]
	v_pk_mul_f32 v[142:143], v[18:19], v[142:143] op_sel_hi:[0,1]
	v_pk_fma_f32 v[110:111], v[190:191], v[200:201], v[134:135]
	v_pk_fma_f32 v[108:109], v[192:193], v[198:199], v[132:133]
	v_pk_mul_f32 v[128:129], v[18:19], v[42:43] op_sel_hi:[0,1]
	v_lshl_add_u64 v[132:133], v[16:17], 0, v[40:41]
	v_cvt_pk_bf16_f32 v40, v138, v139
	v_cvt_pk_bf16_f32 v41, v136, v137
	v_cvt_pk_bf16_f32 v42, v142, v143
	v_cvt_pk_bf16_f32 v43, v140, v141
	v_pk_mul_f32 v[110:111], v[18:19], v[110:111] op_sel_hi:[0,1]
	v_pk_mul_f32 v[108:109], v[18:19], v[108:109] op_sel_hi:[0,1]
	global_store_dwordx4 v[132:133], v[40:43], off
	s_nop 1
	v_cvt_pk_bf16_f32 v40, v108, v109
	v_cvt_pk_bf16_f32 v41, v110, v111
	v_cvt_pk_bf16_f32 v42, v130, v131
	v_cvt_pk_bf16_f32 v43, v128, v129
	global_store_dwordx4 v[132:133], v[40:43], off offset:64
	v_lshlrev_b64 v[128:129], 7, v[180:181]
	v_lshl_add_u64 v[108:109], v[22:23], 0, v[128:129]
	v_lshl_add_u64 v[132:133], v[20:21], 0, v[128:129]
	v_lshlrev_b64 v[252:253], 7, v[176:177]
	v_lshl_add_u64 v[252:253], v[252:253], 0, v[22:23]
	global_load_dwordx4 v[194:197], v[252:253], off offset:16
	global_load_dwordx4 v[198:201], v[252:253], off
	s_mov_b64 s[98:99], 0x400000
	v_lshl_add_u64 v[252:253], v[252:253], 0, s[98:99]
	global_load_dwordx4 v[202:205], v[252:253], off offset:16
	global_load_dwordx4 v[206:209], v[252:253], off
	s_nop 0
	s_nop 0
	s_nop 0
	s_waitcnt vmcnt(10)
	v_pk_mul_f32 v[142:143], v[122:123], v[228:229]
	v_pk_mul_f32 v[140:141], v[120:121], v[230:231]
	v_pk_fma_f32 v[142:143], v[112:113], v[220:221], v[142:143] neg_lo:[0,0,1] neg_hi:[0,0,1]
	v_pk_mul_f32 v[112:113], v[112:113], v[228:229]
	s_waitcnt vmcnt(10)
	v_pk_mul_f32 v[136:137], v[124:125], v[234:235]
	v_pk_mul_f32 v[138:139], v[126:127], v[232:233]
	v_pk_fma_f32 v[140:141], v[114:115], v[222:223], v[140:141] neg_lo:[0,0,1] neg_hi:[0,0,1]
	v_pk_mul_f32 v[114:115], v[114:115], v[230:231]
	v_pk_fma_f32 v[40:41], v[122:123], v[220:221], v[112:113]
	v_pk_fma_f32 v[136:137], v[118:119], v[226:227], v[136:137] neg_lo:[0,0,1] neg_hi:[0,0,1]
	v_pk_fma_f32 v[138:139], v[116:117], v[224:225], v[138:139] neg_lo:[0,0,1] neg_hi:[0,0,1]
	v_pk_mul_f32 v[118:119], v[118:119], v[234:235]
	v_pk_mul_f32 v[116:117], v[116:117], v[232:233]
	v_pk_fma_f32 v[42:43], v[120:121], v[222:223], v[114:115]
	v_pk_mul_f32 v[114:115], v[18:19], v[40:41] op_sel_hi:[0,1]
	v_lshlrev_b64 v[40:41], 10, v[180:181]
	v_pk_mul_f32 v[136:137], v[18:19], v[136:137] op_sel_hi:[0,1]
	v_pk_mul_f32 v[138:139], v[18:19], v[138:139] op_sel_hi:[0,1]
	v_pk_mul_f32 v[140:141], v[18:19], v[140:141] op_sel_hi:[0,1]
	v_pk_mul_f32 v[142:143], v[18:19], v[142:143] op_sel_hi:[0,1]
	v_pk_fma_f32 v[110:111], v[124:125], v[226:227], v[118:119]
	v_pk_fma_f32 v[108:109], v[126:127], v[224:225], v[116:117]
	v_pk_mul_f32 v[112:113], v[18:19], v[42:43] op_sel_hi:[0,1]
	v_lshl_add_u64 v[116:117], v[16:17], 0, v[40:41]
	v_cvt_pk_bf16_f32 v40, v138, v139
	v_cvt_pk_bf16_f32 v41, v136, v137
	v_cvt_pk_bf16_f32 v42, v142, v143
	v_cvt_pk_bf16_f32 v43, v140, v141
	v_pk_mul_f32 v[110:111], v[18:19], v[110:111] op_sel_hi:[0,1]
	v_pk_mul_f32 v[108:109], v[18:19], v[108:109] op_sel_hi:[0,1]
	global_store_dwordx4 v[116:117], v[40:43], off
	s_nop 1
	v_cvt_pk_bf16_f32 v40, v108, v109
	v_cvt_pk_bf16_f32 v41, v110, v111
	v_cvt_pk_bf16_f32 v42, v114, v115
	v_cvt_pk_bf16_f32 v43, v112, v113
	global_store_dwordx4 v[116:117], v[40:43], off offset:64
	v_lshlrev_b64 v[112:113], 7, v[178:179]
	v_lshl_add_u64 v[108:109], v[22:23], 0, v[112:113]
	v_lshl_add_u64 v[116:117], v[20:21], 0, v[112:113]
	v_lshlrev_b64 v[252:253], 7, v[174:175]
	v_lshl_add_u64 v[252:253], v[252:253], 0, v[22:23]
	global_load_dwordx4 v[220:223], v[252:253], off offset:16
	global_load_dwordx4 v[224:227], v[252:253], off
	s_mov_b64 s[98:99], 0x400000
	v_lshl_add_u64 v[252:253], v[252:253], 0, s[98:99]
	global_load_dwordx4 v[228:231], v[252:253], off offset:16
	global_load_dwordx4 v[232:235], v[252:253], off
	s_nop 0
	s_nop 0
	s_nop 0
	s_waitcnt vmcnt(12)
	v_pk_mul_f32 v[126:127], v[104:105], v[244:245]
	s_waitcnt vmcnt(12)
	v_pk_mul_f32 v[120:121], v[100:101], v[250:251]
	v_pk_mul_f32 v[124:125], v[102:103], v[246:247]
	v_pk_fma_f32 v[126:127], v[94:95], v[236:237], v[126:127] neg_lo:[0,0,1] neg_hi:[0,0,1]
	v_pk_mul_f32 v[94:95], v[94:95], v[244:245]
	v_pk_mul_f32 v[122:123], v[106:107], v[248:249]
	v_pk_fma_f32 v[120:121], v[96:97], v[242:243], v[120:121] neg_lo:[0,0,1] neg_hi:[0,0,1]
	v_pk_fma_f32 v[124:125], v[92:93], v[238:239], v[124:125] neg_lo:[0,0,1] neg_hi:[0,0,1]
	v_pk_mul_f32 v[96:97], v[96:97], v[250:251]
	v_pk_mul_f32 v[92:93], v[92:93], v[246:247]
	v_pk_fma_f32 v[40:41], v[104:105], v[236:237], v[94:95]
	v_pk_fma_f32 v[122:123], v[98:99], v[240:241], v[122:123] neg_lo:[0,0,1] neg_hi:[0,0,1]
	v_pk_mul_f32 v[98:99], v[98:99], v[248:249]
	v_pk_fma_f32 v[96:97], v[100:101], v[242:243], v[96:97]
	v_pk_fma_f32 v[42:43], v[102:103], v[238:239], v[92:93]
	v_pk_mul_f32 v[94:95], v[18:19], v[40:41] op_sel_hi:[0,1]
	v_lshlrev_b64 v[40:41], 10, v[178:179]
	v_pk_mul_f32 v[120:121], v[18:19], v[120:121] op_sel_hi:[0,1]
	v_pk_mul_f32 v[122:123], v[18:19], v[122:123] op_sel_hi:[0,1]
	v_pk_mul_f32 v[124:125], v[18:19], v[124:125] op_sel_hi:[0,1]
	v_pk_mul_f32 v[126:127], v[18:19], v[126:127] op_sel_hi:[0,1]
	v_pk_fma_f32 v[98:99], v[106:107], v[240:241], v[98:99]
	v_pk_mul_f32 v[96:97], v[18:19], v[96:97] op_sel_hi:[0,1]
	v_pk_mul_f32 v[92:93], v[18:19], v[42:43] op_sel_hi:[0,1]
	v_lshl_add_u64 v[100:101], v[16:17], 0, v[40:41]
	v_cvt_pk_bf16_f32 v40, v122, v123
	v_cvt_pk_bf16_f32 v41, v120, v121
	v_cvt_pk_bf16_f32 v42, v126, v127
	v_cvt_pk_bf16_f32 v43, v124, v125
	v_pk_mul_f32 v[98:99], v[18:19], v[98:99] op_sel_hi:[0,1]
	global_store_dwordx4 v[100:101], v[40:43], off
	s_nop 1
	v_cvt_pk_bf16_f32 v40, v98, v99
	v_cvt_pk_bf16_f32 v41, v96, v97
	v_cvt_pk_bf16_f32 v42, v94, v95
	v_cvt_pk_bf16_f32 v43, v92, v93
	global_store_dwordx4 v[100:101], v[40:43], off offset:64
	v_lshlrev_b64 v[96:97], 7, v[176:177]
	v_lshl_add_u64 v[92:93], v[22:23], 0, v[96:97]
	v_lshl_add_u64 v[100:101], v[20:21], 0, v[96:97]
	v_lshlrev_b64 v[252:253], 7, v[172:173]
	v_lshl_add_u64 v[252:253], v[252:253], 0, v[22:23]
	global_load_dwordx4 v[236:239], v[252:253], off offset:16
	global_load_dwordx4 v[240:243], v[252:253], off
	s_mov_b64 s[98:99], 0x400000
	v_lshl_add_u64 v[252:253], v[252:253], 0, s[98:99]
	global_load_dwordx4 v[244:247], v[252:253], off offset:16
	global_load_dwordx4 v[248:251], v[252:253], off
	s_nop 0
	s_nop 0
	s_nop 0
	s_waitcnt vmcnt(12)
	v_pk_mul_f32 v[110:111], v[88:89], v[202:203]
	s_waitcnt vmcnt(12)
	v_pk_mul_f32 v[104:105], v[80:81], v[208:209]
	v_pk_mul_f32 v[108:109], v[82:83], v[204:205]
	v_pk_fma_f32 v[110:111], v[78:79], v[194:195], v[110:111] neg_lo:[0,0,1] neg_hi:[0,0,1]
	v_pk_mul_f32 v[78:79], v[78:79], v[202:203]
	v_pk_mul_f32 v[106:107], v[90:91], v[206:207]
	v_pk_fma_f32 v[104:105], v[84:85], v[200:201], v[104:105] neg_lo:[0,0,1] neg_hi:[0,0,1]
	v_pk_fma_f32 v[108:109], v[76:77], v[196:197], v[108:109] neg_lo:[0,0,1] neg_hi:[0,0,1]
	v_pk_mul_f32 v[84:85], v[84:85], v[208:209]
	v_pk_mul_f32 v[76:77], v[76:77], v[204:205]
	v_pk_fma_f32 v[40:41], v[88:89], v[194:195], v[78:79]
	v_pk_fma_f32 v[106:107], v[86:87], v[198:199], v[106:107] neg_lo:[0,0,1] neg_hi:[0,0,1]
	v_pk_mul_f32 v[86:87], v[86:87], v[206:207]
	v_pk_fma_f32 v[80:81], v[80:81], v[200:201], v[84:85]
	v_pk_fma_f32 v[42:43], v[82:83], v[196:197], v[76:77]
	v_pk_mul_f32 v[78:79], v[18:19], v[40:41] op_sel_hi:[0,1]
	v_lshlrev_b64 v[40:41], 10, v[176:177]
	v_pk_mul_f32 v[104:105], v[18:19], v[104:105] op_sel_hi:[0,1]
	v_pk_mul_f32 v[106:107], v[18:19], v[106:107] op_sel_hi:[0,1]
	v_pk_mul_f32 v[108:109], v[18:19], v[108:109] op_sel_hi:[0,1]
	v_pk_mul_f32 v[110:111], v[18:19], v[110:111] op_sel_hi:[0,1]
	v_pk_fma_f32 v[84:85], v[90:91], v[198:199], v[86:87]
	v_pk_mul_f32 v[80:81], v[18:19], v[80:81] op_sel_hi:[0,1]
	v_pk_mul_f32 v[76:77], v[18:19], v[42:43] op_sel_hi:[0,1]
	v_lshl_add_u64 v[82:83], v[16:17], 0, v[40:41]
	v_cvt_pk_bf16_f32 v40, v106, v107
	v_cvt_pk_bf16_f32 v41, v104, v105
	v_cvt_pk_bf16_f32 v42, v110, v111
	v_cvt_pk_bf16_f32 v43, v108, v109
	v_pk_mul_f32 v[84:85], v[18:19], v[84:85] op_sel_hi:[0,1]
	global_store_dwordx4 v[82:83], v[40:43], off
	s_nop 1
	v_cvt_pk_bf16_f32 v40, v84, v85
	v_cvt_pk_bf16_f32 v41, v80, v81
	v_cvt_pk_bf16_f32 v42, v78, v79
	v_cvt_pk_bf16_f32 v43, v76, v77
	global_store_dwordx4 v[82:83], v[40:43], off offset:64
	v_lshlrev_b64 v[80:81], 7, v[174:175]
	v_lshl_add_u64 v[76:77], v[22:23], 0, v[80:81]
	v_lshl_add_u64 v[84:85], v[20:21], 0, v[80:81]
	v_lshlrev_b64 v[252:253], 7, v[170:171]
	v_lshl_add_u64 v[252:253], v[252:253], 0, v[22:23]
	global_load_dwordx4 v[194:197], v[252:253], off offset:16
	global_load_dwordx4 v[198:201], v[252:253], off
	s_mov_b64 s[98:99], 0x400000
	v_lshl_add_u64 v[252:253], v[252:253], 0, s[98:99]
	global_load_dwordx4 v[202:205], v[252:253], off offset:16
	global_load_dwordx4 v[206:209], v[252:253], off
	s_nop 0
	s_nop 0
	s_nop 0
	s_waitcnt vmcnt(12)
	v_pk_mul_f32 v[94:95], v[72:73], v[228:229]
	s_waitcnt vmcnt(12)
	v_pk_mul_f32 v[88:89], v[68:69], v[234:235]
	v_pk_mul_f32 v[92:93], v[70:71], v[230:231]
	v_pk_fma_f32 v[94:95], v[62:63], v[220:221], v[94:95] neg_lo:[0,0,1] neg_hi:[0,0,1]
	v_pk_mul_f32 v[62:63], v[62:63], v[228:229]
	v_pk_mul_f32 v[90:91], v[74:75], v[232:233]
	v_pk_fma_f32 v[88:89], v[64:65], v[226:227], v[88:89] neg_lo:[0,0,1] neg_hi:[0,0,1]
	v_pk_fma_f32 v[92:93], v[60:61], v[222:223], v[92:93] neg_lo:[0,0,1] neg_hi:[0,0,1]
	v_pk_mul_f32 v[64:65], v[64:65], v[234:235]
	v_pk_mul_f32 v[60:61], v[60:61], v[230:231]
	v_pk_fma_f32 v[40:41], v[72:73], v[220:221], v[62:63]
	v_pk_fma_f32 v[90:91], v[66:67], v[224:225], v[90:91] neg_lo:[0,0,1] neg_hi:[0,0,1]
	v_pk_mul_f32 v[66:67], v[66:67], v[232:233]
	v_pk_fma_f32 v[64:65], v[68:69], v[226:227], v[64:65]
	v_pk_fma_f32 v[42:43], v[70:71], v[222:223], v[60:61]
	v_pk_mul_f32 v[62:63], v[18:19], v[40:41] op_sel_hi:[0,1]
	v_lshlrev_b64 v[40:41], 10, v[174:175]
	v_pk_mul_f32 v[88:89], v[18:19], v[88:89] op_sel_hi:[0,1]
	v_pk_mul_f32 v[90:91], v[18:19], v[90:91] op_sel_hi:[0,1]
	v_pk_mul_f32 v[92:93], v[18:19], v[92:93] op_sel_hi:[0,1]
	v_pk_mul_f32 v[94:95], v[18:19], v[94:95] op_sel_hi:[0,1]
	v_pk_fma_f32 v[66:67], v[74:75], v[224:225], v[66:67]
	v_pk_mul_f32 v[64:65], v[18:19], v[64:65] op_sel_hi:[0,1]
	v_pk_mul_f32 v[60:61], v[18:19], v[42:43] op_sel_hi:[0,1]
	v_lshl_add_u64 v[68:69], v[16:17], 0, v[40:41]
	v_cvt_pk_bf16_f32 v40, v90, v91
	v_cvt_pk_bf16_f32 v41, v88, v89
	v_cvt_pk_bf16_f32 v42, v94, v95
	v_cvt_pk_bf16_f32 v43, v92, v93
	v_pk_mul_f32 v[66:67], v[18:19], v[66:67] op_sel_hi:[0,1]
	global_store_dwordx4 v[68:69], v[40:43], off
	s_nop 1
	v_cvt_pk_bf16_f32 v40, v66, v67
	v_cvt_pk_bf16_f32 v41, v64, v65
	v_cvt_pk_bf16_f32 v42, v62, v63
	v_cvt_pk_bf16_f32 v43, v60, v61
	global_store_dwordx4 v[68:69], v[40:43], off offset:64
	v_lshlrev_b64 v[64:65], 7, v[172:173]
	v_lshl_add_u64 v[60:61], v[22:23], 0, v[64:65]
	v_lshl_add_u64 v[68:69], v[20:21], 0, v[64:65]
	v_lshlrev_b64 v[252:253], 7, v[168:169]
	v_lshl_add_u64 v[252:253], v[252:253], 0, v[22:23]
	global_load_dwordx4 v[220:223], v[252:253], off offset:16
	global_load_dwordx4 v[224:227], v[252:253], off
	s_mov_b64 s[98:99], 0x400000
	v_lshl_add_u64 v[252:253], v[252:253], 0, s[98:99]
	global_load_dwordx4 v[228:231], v[252:253], off offset:16
	global_load_dwordx4 v[232:235], v[252:253], off
	s_nop 0
	s_nop 0
	s_nop 0
	s_waitcnt vmcnt(12)
	v_pk_mul_f32 v[78:79], v[56:57], v[244:245]
	s_waitcnt vmcnt(12)
	v_pk_mul_f32 v[72:73], v[48:49], v[250:251]
	v_pk_mul_f32 v[76:77], v[50:51], v[246:247]
	v_pk_fma_f32 v[78:79], v[46:47], v[236:237], v[78:79] neg_lo:[0,0,1] neg_hi:[0,0,1]
	v_pk_mul_f32 v[46:47], v[46:47], v[244:245]
	v_pk_mul_f32 v[74:75], v[58:59], v[248:249]
	v_pk_fma_f32 v[72:73], v[54:55], v[242:243], v[72:73] neg_lo:[0,0,1] neg_hi:[0,0,1]
	v_pk_fma_f32 v[76:77], v[44:45], v[238:239], v[76:77] neg_lo:[0,0,1] neg_hi:[0,0,1]
	v_pk_mul_f32 v[54:55], v[54:55], v[250:251]
	v_pk_mul_f32 v[44:45], v[44:45], v[246:247]
	v_pk_fma_f32 v[40:41], v[56:57], v[236:237], v[46:47]
	v_pk_fma_f32 v[74:75], v[52:53], v[240:241], v[74:75] neg_lo:[0,0,1] neg_hi:[0,0,1]
	v_pk_mul_f32 v[52:53], v[52:53], v[248:249]
	v_pk_fma_f32 v[48:49], v[48:49], v[242:243], v[54:55]
	v_pk_fma_f32 v[42:43], v[50:51], v[238:239], v[44:45]
	v_pk_mul_f32 v[46:47], v[18:19], v[40:41] op_sel_hi:[0,1]
	v_lshlrev_b64 v[40:41], 10, v[172:173]
	v_pk_mul_f32 v[72:73], v[18:19], v[72:73] op_sel_hi:[0,1]
	v_pk_mul_f32 v[74:75], v[18:19], v[74:75] op_sel_hi:[0,1]
	v_pk_mul_f32 v[76:77], v[18:19], v[76:77] op_sel_hi:[0,1]
	v_pk_mul_f32 v[78:79], v[18:19], v[78:79] op_sel_hi:[0,1]
	v_pk_fma_f32 v[52:53], v[58:59], v[240:241], v[52:53]
	v_pk_mul_f32 v[48:49], v[18:19], v[48:49] op_sel_hi:[0,1]
	v_pk_mul_f32 v[44:45], v[18:19], v[42:43] op_sel_hi:[0,1]
	v_lshl_add_u64 v[50:51], v[16:17], 0, v[40:41]
	v_cvt_pk_bf16_f32 v40, v74, v75
	v_cvt_pk_bf16_f32 v41, v72, v73
	v_cvt_pk_bf16_f32 v42, v78, v79
	v_cvt_pk_bf16_f32 v43, v76, v77
	v_pk_mul_f32 v[52:53], v[18:19], v[52:53] op_sel_hi:[0,1]
	global_store_dwordx4 v[50:51], v[40:43], off
	s_nop 1
	v_cvt_pk_bf16_f32 v40, v52, v53
	v_cvt_pk_bf16_f32 v41, v48, v49
	v_cvt_pk_bf16_f32 v42, v46, v47
	v_cvt_pk_bf16_f32 v43, v44, v45
	global_store_dwordx4 v[50:51], v[40:43], off offset:64
	v_lshlrev_b64 v[48:49], 7, v[170:171]
	v_lshl_add_u64 v[44:45], v[22:23], 0, v[48:49]
	v_lshl_add_u64 v[52:53], v[20:21], 0, v[48:49]
	s_nop 0
	s_nop 0
	s_nop 0
	s_waitcnt vmcnt(8)
	v_pk_mul_f32 v[60:61], v[34:35], v[204:205]
	s_waitcnt vmcnt(8)
	v_pk_mul_f32 v[56:57], v[32:33], v[208:209]
	v_pk_mul_f32 v[58:59], v[38:39], v[206:207]
	v_pk_mul_f32 v[62:63], v[36:37], v[202:203]
	v_pk_fma_f32 v[60:61], v[24:25], v[196:197], v[60:61] neg_lo:[0,0,1] neg_hi:[0,0,1]
	v_pk_mul_f32 v[24:25], v[24:25], v[204:205]
	v_pk_fma_f32 v[56:57], v[28:29], v[200:201], v[56:57] neg_lo:[0,0,1] neg_hi:[0,0,1]
	v_pk_fma_f32 v[58:59], v[30:31], v[198:199], v[58:59] neg_lo:[0,0,1] neg_hi:[0,0,1]
	v_pk_fma_f32 v[62:63], v[26:27], v[194:195], v[62:63] neg_lo:[0,0,1] neg_hi:[0,0,1]
	v_pk_mul_f32 v[28:29], v[28:29], v[208:209]
	v_pk_mul_f32 v[30:31], v[30:31], v[206:207]
	v_pk_mul_f32 v[26:27], v[26:27], v[202:203]
	v_pk_fma_f32 v[24:25], v[34:35], v[196:197], v[24:25]
	v_pk_fma_f32 v[28:29], v[32:33], v[200:201], v[28:29]
	v_pk_fma_f32 v[30:31], v[38:39], v[198:199], v[30:31]
	v_pk_fma_f32 v[26:27], v[36:37], v[194:195], v[26:27]
	v_pk_mul_f32 v[32:33], v[18:19], v[24:25] op_sel_hi:[0,1]
	v_lshlrev_b64 v[24:25], 10, v[170:171]
	v_pk_mul_f32 v[56:57], v[18:19], v[56:57] op_sel_hi:[0,1]
	v_pk_mul_f32 v[58:59], v[18:19], v[58:59] op_sel_hi:[0,1]
	v_pk_mul_f32 v[60:61], v[18:19], v[60:61] op_sel_hi:[0,1]
	v_pk_mul_f32 v[62:63], v[18:19], v[62:63] op_sel_hi:[0,1]
	v_pk_mul_f32 v[30:31], v[18:19], v[30:31] op_sel_hi:[0,1]
	v_pk_mul_f32 v[34:35], v[18:19], v[26:27] op_sel_hi:[0,1]
	v_lshl_add_u64 v[36:37], v[16:17], 0, v[24:25]
	v_cvt_pk_bf16_f32 v24, v58, v59
	v_cvt_pk_bf16_f32 v25, v56, v57
	v_cvt_pk_bf16_f32 v26, v62, v63
	v_cvt_pk_bf16_f32 v27, v60, v61
	v_pk_mul_f32 v[28:29], v[18:19], v[28:29] op_sel_hi:[0,1]
	global_store_dwordx4 v[36:37], v[24:27], off
	s_nop 1
	v_cvt_pk_bf16_f32 v24, v30, v31
	v_cvt_pk_bf16_f32 v25, v28, v29
	v_cvt_pk_bf16_f32 v26, v34, v35
	v_cvt_pk_bf16_f32 v27, v32, v33
	global_store_dwordx4 v[36:37], v[24:27], off offset:64
	v_lshlrev_b64 v[30:31], 7, v[168:169]
	v_lshl_add_u64 v[20:21], v[20:21], 0, v[30:31]
	v_lshl_add_u64 v[26:27], v[22:23], 0, v[30:31]
	s_nop 0
	s_nop 0
	s_waitcnt vmcnt(4)
	v_pk_mul_f32 v[40:41], v[2:3], v[230:231]
	s_waitcnt vmcnt(4)
	v_pk_mul_f32 v[20:21], v[6:7], v[234:235]
	v_pk_mul_f32 v[38:39], v[4:5], v[232:233]
	v_pk_fma_f32 v[20:21], v[10:11], v[226:227], v[20:21] neg_lo:[0,0,1] neg_hi:[0,0,1]
	v_pk_mul_f32 v[10:11], v[10:11], v[234:235]
	v_pk_fma_f32 v[38:39], v[14:15], v[224:225], v[38:39] neg_lo:[0,0,1] neg_hi:[0,0,1]
	v_pk_mul_f32 v[14:15], v[14:15], v[232:233]
	v_pk_fma_f32 v[6:7], v[6:7], v[226:227], v[10:11]
	v_pk_fma_f32 v[10:11], v[4:5], v[224:225], v[14:15]
	v_pk_mul_f32 v[4:5], v[18:19], v[6:7] op_sel_hi:[0,1]
	v_pk_mul_f32 v[6:7], v[8:9], v[230:231]
	v_pk_fma_f32 v[40:41], v[8:9], v[222:223], v[40:41] neg_lo:[0,0,1] neg_hi:[0,0,1]
	v_pk_mul_f32 v[8:9], v[12:13], v[228:229]
	v_pk_fma_f32 v[2:3], v[2:3], v[222:223], v[6:7]
	v_pk_mul_f32 v[42:43], v[0:1], v[228:229]
	v_pk_fma_f32 v[6:7], v[0:1], v[220:221], v[8:9]
	v_pk_mul_f32 v[0:1], v[18:19], v[2:3] op_sel_hi:[0,1]
	v_lshlrev_b64 v[2:3], 10, v[168:169]
	v_pk_fma_f32 v[42:43], v[12:13], v[220:221], v[42:43] neg_lo:[0,0,1] neg_hi:[0,0,1]
	v_lshl_add_u64 v[14:15], v[16:17], 0, v[2:3]
	v_pk_mul_f32 v[20:21], v[18:19], v[20:21] op_sel_hi:[0,1]
	v_pk_mul_f32 v[38:39], v[18:19], v[38:39] op_sel_hi:[0,1]
	v_pk_mul_f32 v[40:41], v[18:19], v[40:41] op_sel_hi:[0,1]
	v_pk_mul_f32 v[42:43], v[18:19], v[42:43] op_sel_hi:[0,1]
	v_pk_mul_f32 v[10:11], v[18:19], v[10:11] op_sel_hi:[0,1]
	v_pk_mul_f32 v[12:13], v[18:19], v[6:7] op_sel_hi:[0,1]
	v_cvt_pk_bf16_f32 v6, v38, v39
	v_cvt_pk_bf16_f32 v7, v20, v21
	v_cvt_pk_bf16_f32 v8, v42, v43
	v_cvt_pk_bf16_f32 v9, v40, v41
	global_store_dwordx4 v[14:15], v[6:9], off
	v_cvt_pk_bf16_f32 v2, v10, v11
	v_cvt_pk_bf16_f32 v3, v4, v5
	v_cvt_pk_bf16_f32 v4, v12, v13
	v_cvt_pk_bf16_f32 v5, v0, v1
	global_store_dwordx4 v[14:15], v[2:5], off offset:64
	s_andn2_b64 vcc, exec, s[8:9]
	s_mov_b64 s[2:3], -1
	s_cbranch_vccnz .LBB0_700
